# tswait2: in-proj tile switch: first two waits of the peeled first K iteration relaxed to vmcnt(24) from the second tile on (the epilogue's 16 stores are not waited for); on top of itemwait
# baseline (speedup 1.0000x reference)
.LBB0_475:
	s_ashr_i32 s29, s28, 31
	s_lshl_b64 s[16:17], s[28:29], 19
	s_add_u32 s30, s92, s16
	s_addc_u32 s31, s93, s17
	s_and_b64 s[16:17], s[8:9], exec
	s_cselect_b32 s5, s31, s15
	s_cselect_b32 s13, s30, s14
	s_ashr_i32 s25, s24, 31
	s_lshl_b64 s[16:17], s[24:25], 19
	v_readlane_b32 s34, v254, 43
	v_readlane_b32 s35, v254, 44
	s_add_u32 s36, s34, s16
	s_addc_u32 s37, s35, s17
	s_and_b64 s[16:17], s[8:9], exec
	s_cselect_b32 s25, s37, s11
	s_cselect_b32 s29, s36, s10
	s_add_u32 s34, s10, 0x100
	s_addc_u32 s35, s11, 0
	s_add_u32 s10, s14, 0x40080
	s_addc_u32 s11, s15, 0
	s_mov_b32 s38, -2
	s_waitcnt vmcnt(0)
	s_add_u32 s14, s10, 0xfffc0080
	s_addc_u32 s15, s11, -1
	s_add_i32 s39, 0, 0x10000
	s_cmp_eq_u32 s38, 12
	s_cselect_b32 s17, s5, s15
	s_cselect_b32 s16, s13, s14
	v_add_u32_e32 v0, s39, v251
	s_cselect_b32 s15, s25, s35
	s_cselect_b32 s14, s29, s34
	s_add_i32 s42, 0, 0x14000
	ds_read_b128 v[2:5], v0
	ds_read_b128 v[6:9], v0 offset:1024
	ds_read_b128 v[34:37], v0 offset:2048
	ds_read_b128 v[38:41], v0 offset:3072
	v_add_u32_e32 v0, s42, v251
	ds_read_b128 v[50:53], v0
	ds_read_b128 v[54:57], v0 offset:1024
	ds_read_b128 v[66:69], v0 offset:2048
	ds_read_b128 v[70:73], v0 offset:3072
	v_lshl_add_u64 v[138:139], s[10:11], 0, v[228:229]
	s_add_i32 m0, s47, 0xc000
	ds_read_b128 v[82:85], v241
	ds_read_b128 v[86:89], v241 offset:1024
	ds_read_b128 v[98:101], v241 offset:2048
	ds_read_b128 v[102:105], v241 offset:3072
	ds_read_b128 v[114:117], v241 offset:4096
	ds_read_b128 v[118:121], v241 offset:5120
	ds_read_b128 v[122:125], v241 offset:6144
	ds_read_b128 v[126:129], v241 offset:7168
	global_load_lds_dwordx4 v[138:139], off
	v_lshl_add_u64 v[138:139], s[10:11], 0, v[226:227]
	s_add_i32 m0, s47, 0xe000
	s_nop 0
	global_load_lds_dwordx4 v[138:139], off
	s_cmp_eq_u32 s71, 1
	s_cbranch_scc1 .Ltw2_f0
	s_waitcnt vmcnt(24)
	s_branch .Ltw2_j0

.Ltw2_j0:
	s_waitcnt lgkmcnt(0)
	s_barrier
	s_setprio 1
	s_waitcnt lgkmcnt(0)
	v_mfma_f32_16x16x32_bf16 v[190:193], v[2:5], v[114:117], 0
	v_mfma_f32_16x16x32_bf16 v[186:189], v[34:37], v[114:117], 0
	v_mfma_f32_16x16x32_bf16 v[182:185], v[2:5], v[122:125], 0
	v_mfma_f32_16x16x32_bf16 v[178:181], v[34:37], v[122:125], 0
	v_mfma_f32_16x16x32_bf16 v[138:141], v[2:5], v[82:85], 0
	v_mfma_f32_16x16x32_bf16 v[142:145], v[34:37], v[82:85], 0
	v_mfma_f32_16x16x32_bf16 v[162:165], v[2:5], v[98:101], 0
	v_mfma_f32_16x16x32_bf16 v[166:169], v[34:37], v[98:101], 0
	v_mfma_f32_16x16x32_bf16 v[190:193], v[6:9], v[118:121], v[190:193]
	v_mfma_f32_16x16x32_bf16 v[186:189], v[38:41], v[118:121], v[186:189]
	v_mfma_f32_16x16x32_bf16 v[182:185], v[6:9], v[126:129], v[182:185]
	v_mfma_f32_16x16x32_bf16 v[178:181], v[38:41], v[126:129], v[178:181]
	v_mfma_f32_16x16x32_bf16 v[138:141], v[6:9], v[86:89], v[138:141]
	v_mfma_f32_16x16x32_bf16 v[142:145], v[38:41], v[86:89], v[142:145]
	v_mfma_f32_16x16x32_bf16 v[162:165], v[6:9], v[102:105], v[162:165]
	v_mfma_f32_16x16x32_bf16 v[166:169], v[38:41], v[102:105], v[166:169]
	s_setprio 0
	s_setprio 1
	v_mfma_f32_16x16x32_bf16 v[110:113], v[50:53], v[82:85], 0
	v_mfma_f32_16x16x32_bf16 v[82:85], v[66:69], v[82:85], 0
	v_mfma_f32_16x16x32_bf16 v[90:93], v[66:69], v[98:101], 0
	v_mfma_f32_16x16x32_bf16 v[78:81], v[50:53], v[114:117], 0
	v_mfma_f32_16x16x32_bf16 v[74:77], v[66:69], v[114:117], 0
	v_mfma_f32_16x16x32_bf16 v[62:65], v[50:53], v[122:125], 0
	v_mfma_f32_16x16x32_bf16 v[58:61], v[66:69], v[122:125], 0
	v_mfma_f32_16x16x32_bf16 v[110:113], v[54:57], v[86:89], v[110:113]
	v_mfma_f32_16x16x32_bf16 v[82:85], v[70:73], v[86:89], v[82:85]
	v_mfma_f32_16x16x32_bf16 v[86:89], v[50:53], v[98:101], 0
	v_mfma_f32_16x16x32_bf16 v[90:93], v[70:73], v[102:105], v[90:93]
	v_mfma_f32_16x16x32_bf16 v[78:81], v[54:57], v[118:121], v[78:81]
	v_mfma_f32_16x16x32_bf16 v[74:77], v[70:73], v[118:121], v[74:77]
	v_mfma_f32_16x16x32_bf16 v[62:65], v[54:57], v[126:129], v[62:65]
	v_mfma_f32_16x16x32_bf16 v[58:61], v[70:73], v[126:129], v[58:61]
	v_mfma_f32_16x16x32_bf16 v[86:89], v[54:57], v[102:105], v[86:89]
	s_setprio 0
	s_barrier
	s_add_i32 s39, s39, s46
	v_lshl_add_u64 v[230:231], s[14:15], 0, v[212:213]
	s_mov_b32 m0, s39
	ds_read_b128 v[94:97], v241 offset:16384
	ds_read_b128 v[98:101], v241 offset:17408
	ds_read_b128 v[102:105], v241 offset:18432
	ds_read_b128 v[106:109], v241 offset:19456
	ds_read_b128 v[114:117], v241 offset:20480
	ds_read_b128 v[118:121], v241 offset:21504
	ds_read_b128 v[122:125], v241 offset:22528
	ds_read_b128 v[126:129], v241 offset:23552
	global_load_lds_dwordx4 v[230:231], off
	s_add_i32 m0, s39, 0x2000
	s_add_u32 s40, s14, 0x40000
	v_lshl_add_u64 v[232:233], s[14:15], 0, v[216:217]
	s_addc_u32 s41, s15, 0
	s_add_i32 s39, s42, s46
	global_load_lds_dwordx4 v[232:233], off
	v_lshl_add_u64 v[194:195], s[40:41], 0, v[212:213]
	s_mov_b32 m0, s39
	v_lshl_add_u64 v[234:235], s[16:17], 0, v[210:211]
	global_load_lds_dwordx4 v[194:195], off
	v_lshl_add_u64 v[194:195], s[40:41], 0, v[216:217]
	s_add_i32 m0, s39, 0x2000
	v_lshl_add_u64 v[236:237], s[16:17], 0, v[214:215]
	global_load_lds_dwordx4 v[194:195], off
	s_mov_b32 m0, s47
	s_nop 0
	global_load_lds_dwordx4 v[234:235], off
	s_mov_b32 m0, s48
	s_nop 0
	global_load_lds_dwordx4 v[236:237], off
	s_cmp_eq_u32 s71, 1
	s_cbranch_scc1 .Ltw2_f1
	s_waitcnt vmcnt(24)
	s_branch .Ltw2_j1

.Ltw2_j1:
	s_waitcnt lgkmcnt(0)
	s_barrier
	s_setprio 1
	s_waitcnt lgkmcnt(0)
	v_mfma_f32_16x16x32_bf16 v[174:177], v[2:5], v[94:97], 0
	v_mfma_f32_16x16x32_bf16 v[170:173], v[34:37], v[94:97], 0
	v_mfma_f32_16x16x32_bf16 v[158:161], v[2:5], v[102:105], 0
	v_mfma_f32_16x16x32_bf16 v[154:157], v[34:37], v[102:105], 0
	v_mfma_f32_16x16x32_bf16 v[150:153], v[2:5], v[114:117], 0
	v_mfma_f32_16x16x32_bf16 v[146:149], v[34:37], v[114:117], 0
	v_mfma_f32_16x16x32_bf16 v[2:5], v[2:5], v[122:125], 0
	v_mfma_f32_16x16x32_bf16 v[174:177], v[6:9], v[98:101], v[174:177]
	v_mfma_f32_16x16x32_bf16 v[170:173], v[38:41], v[98:101], v[170:173]
	v_mfma_f32_16x16x32_bf16 v[158:161], v[6:9], v[106:109], v[158:161]
	v_mfma_f32_16x16x32_bf16 v[154:157], v[38:41], v[106:109], v[154:157]
	v_mfma_f32_16x16x32_bf16 v[150:153], v[6:9], v[118:121], v[150:153]
	v_mfma_f32_16x16x32_bf16 v[146:149], v[38:41], v[118:121], v[146:149]
	v_mfma_f32_16x16x32_bf16 v[2:5], v[6:9], v[126:129], v[2:5]
	v_mfma_f32_16x16x32_bf16 v[6:9], v[34:37], v[122:125], 0
	v_mfma_f32_16x16x32_bf16 v[6:9], v[38:41], v[126:129], v[6:9]
	s_setprio 0
	s_setprio 1
	v_mfma_f32_16x16x32_bf16 v[30:33], v[50:53], v[102:105], 0
	v_mfma_f32_16x16x32_bf16 v[26:29], v[66:69], v[102:105], 0
	v_mfma_f32_16x16x32_bf16 v[22:25], v[50:53], v[114:117], 0
	v_mfma_f32_16x16x32_bf16 v[18:21], v[66:69], v[114:117], 0
	v_mfma_f32_16x16x32_bf16 v[14:17], v[50:53], v[122:125], 0
	v_mfma_f32_16x16x32_bf16 v[10:13], v[66:69], v[122:125], 0
	v_mfma_f32_16x16x32_bf16 v[34:37], v[50:53], v[94:97], 0
	v_mfma_f32_16x16x32_bf16 v[38:41], v[66:69], v[94:97], 0
	v_mfma_f32_16x16x32_bf16 v[30:33], v[54:57], v[106:109], v[30:33]
	v_mfma_f32_16x16x32_bf16 v[26:29], v[70:73], v[106:109], v[26:29]
	v_mfma_f32_16x16x32_bf16 v[22:25], v[54:57], v[118:121], v[22:25]
	v_mfma_f32_16x16x32_bf16 v[18:21], v[70:73], v[118:121], v[18:21]
	v_mfma_f32_16x16x32_bf16 v[14:17], v[54:57], v[126:129], v[14:17]
	v_mfma_f32_16x16x32_bf16 v[10:13], v[70:73], v[126:129], v[10:13]
	v_mfma_f32_16x16x32_bf16 v[34:37], v[54:57], v[98:101], v[34:37]
	v_mfma_f32_16x16x32_bf16 v[38:41], v[70:73], v[98:101], v[38:41]
	s_setprio 0
	s_barrier
	s_add_i32 s39, 0, 0x18000
	v_add_u32_e32 v0, s39, v251
	s_add_i32 s40, 0, 0x1c000
	ds_read_b128 v[42:45], v0
	ds_read_b128 v[46:49], v0 offset:1024
	ds_read_b128 v[50:53], v0 offset:2048
	ds_read_b128 v[54:57], v0 offset:3072
	v_add_u32_e32 v0, s40, v251
	ds_read_b128 v[66:69], v0
	ds_read_b128 v[70:73], v0 offset:1024
	ds_read_b128 v[98:101], v0 offset:2048
	ds_read_b128 v[102:105], v0 offset:3072
	s_add_u32 s16, s16, 0x40000
	s_addc_u32 s17, s17, 0
	s_mov_b32 m0, s49
	v_lshl_add_u64 v[194:195], s[16:17], 0, v[210:211]
	ds_read_b128 v[94:97], v241 offset:32768
	ds_read_b128 v[106:109], v241 offset:33792
	ds_read_b128 v[114:117], v241 offset:34816
	ds_read_b128 v[118:121], v241 offset:35840
	ds_read_b128 v[122:125], v241 offset:36864
	ds_read_b128 v[126:129], v241 offset:37888
	ds_read_b128 v[130:133], v241 offset:38912
	ds_read_b128 v[134:137], v241 offset:39936
	global_load_lds_dwordx4 v[194:195], off
	v_lshl_add_u64 v[194:195], s[16:17], 0, v[214:215]
	s_mov_b32 m0, s61
	s_nop 0
	global_load_lds_dwordx4 v[194:195], off
	s_waitcnt vmcnt(8)
	s_waitcnt lgkmcnt(0)
	s_barrier
	s_setprio 1
	s_waitcnt lgkmcnt(0)
	v_mfma_f32_16x16x32_bf16 v[138:141], v[42:45], v[94:97], v[138:141]
	v_mfma_f32_16x16x32_bf16 v[206:209], v[46:49], v[106:109], v[138:141]
	v_mfma_f32_16x16x32_bf16 v[138:141], v[50:53], v[94:97], v[142:145]
	v_mfma_f32_16x16x32_bf16 v[202:205], v[54:57], v[106:109], v[138:141]
	v_mfma_f32_16x16x32_bf16 v[138:141], v[42:45], v[114:117], v[162:165]
	v_mfma_f32_16x16x32_bf16 v[198:201], v[46:49], v[118:121], v[138:141]
	v_mfma_f32_16x16x32_bf16 v[138:141], v[50:53], v[114:117], v[166:169]
	v_mfma_f32_16x16x32_bf16 v[194:197], v[54:57], v[118:121], v[138:141]
	v_mfma_f32_16x16x32_bf16 v[138:141], v[42:45], v[122:125], v[190:193]
	v_mfma_f32_16x16x32_bf16 v[190:193], v[46:49], v[126:129], v[138:141]
	v_mfma_f32_16x16x32_bf16 v[138:141], v[50:53], v[122:125], v[186:189]
	v_mfma_f32_16x16x32_bf16 v[186:189], v[54:57], v[126:129], v[138:141]
	v_mfma_f32_16x16x32_bf16 v[138:141], v[42:45], v[130:133], v[182:185]
	v_mfma_f32_16x16x32_bf16 v[182:185], v[46:49], v[134:137], v[138:141]
	v_mfma_f32_16x16x32_bf16 v[138:141], v[50:53], v[130:133], v[178:181]
	v_mfma_f32_16x16x32_bf16 v[178:181], v[54:57], v[134:137], v[138:141]
	s_setprio 0
	s_setprio 1
	v_mfma_f32_16x16x32_bf16 v[110:113], v[66:69], v[94:97], v[110:113]
	v_mfma_f32_16x16x32_bf16 v[82:85], v[98:101], v[94:97], v[82:85]
	v_mfma_f32_16x16x32_bf16 v[110:113], v[70:73], v[106:109], v[110:113]
	v_mfma_f32_16x16x32_bf16 v[106:109], v[102:105], v[106:109], v[82:85]
	v_mfma_f32_16x16x32_bf16 v[82:85], v[66:69], v[114:117], v[86:89]
	v_mfma_f32_16x16x32_bf16 v[94:97], v[70:73], v[118:121], v[82:85]
	v_mfma_f32_16x16x32_bf16 v[82:85], v[98:101], v[114:117], v[90:93]
	v_mfma_f32_16x16x32_bf16 v[78:81], v[66:69], v[122:125], v[78:81]
	v_mfma_f32_16x16x32_bf16 v[74:77], v[98:101], v[122:125], v[74:77]
	v_mfma_f32_16x16x32_bf16 v[62:65], v[66:69], v[130:133], v[62:65]
	v_mfma_f32_16x16x32_bf16 v[58:61], v[98:101], v[130:133], v[58:61]
	v_mfma_f32_16x16x32_bf16 v[90:93], v[102:105], v[118:121], v[82:85]
	v_mfma_f32_16x16x32_bf16 v[78:81], v[70:73], v[126:129], v[78:81]
	v_mfma_f32_16x16x32_bf16 v[74:77], v[102:105], v[126:129], v[74:77]
	v_mfma_f32_16x16x32_bf16 v[62:65], v[70:73], v[134:137], v[62:65]
	v_mfma_f32_16x16x32_bf16 v[58:61], v[102:105], v[134:137], v[58:61]
	s_setprio 0
	s_barrier
	s_add_i32 s16, s39, s46
	v_lshl_add_u64 v[130:131], v[230:231], 0, s[76:77]
	s_mov_b32 m0, s16
	ds_read_b128 v[82:85], v241 offset:49152
	ds_read_b128 v[86:89], v241 offset:50176
	ds_read_b128 v[114:117], v241 offset:51200
	ds_read_b128 v[118:121], v241 offset:52224
	ds_read_b128 v[122:125], v241 offset:53248
	ds_read_b128 v[126:129], v241 offset:54272
	ds_read_b128 v[138:141], v241 offset:55296
	ds_read_b128 v[142:145], v241 offset:56320
	global_load_lds_dwordx4 v[130:131], off
	s_add_i32 m0, s16, 0x2000
	s_add_u32 s14, s14, 0x40080
	v_lshl_add_u64 v[130:131], v[232:233], 0, s[76:77]
	s_addc_u32 s15, s15, 0
	s_add_i32 s16, s40, s46
	global_load_lds_dwordx4 v[130:131], off
	v_lshl_add_u64 v[130:131], s[14:15], 0, v[212:213]
	s_mov_b32 m0, s16
	s_nop 0
	global_load_lds_dwordx4 v[130:131], off
	v_lshl_add_u64 v[130:131], s[14:15], 0, v[216:217]
	s_add_i32 m0, s16, 0x2000
	s_nop 0
	global_load_lds_dwordx4 v[130:131], off
	v_lshl_add_u64 v[130:131], v[234:235], 0, s[76:77]
	s_mov_b32 m0, s63
	s_nop 0
	global_load_lds_dwordx4 v[130:131], off
	v_lshl_add_u64 v[130:131], v[236:237], 0, s[76:77]
	s_mov_b32 m0, s70
	s_nop 0
	global_load_lds_dwordx4 v[130:131], off
	s_waitcnt vmcnt(8)
	s_waitcnt lgkmcnt(0)
	s_barrier
	s_setprio 1
	s_waitcnt lgkmcnt(0)
	v_mfma_f32_16x16x32_bf16 v[130:133], v[42:45], v[82:85], v[174:177]
	v_mfma_f32_16x16x32_bf16 v[174:177], v[46:49], v[86:89], v[130:133]
	v_mfma_f32_16x16x32_bf16 v[130:133], v[50:53], v[82:85], v[170:173]
	v_mfma_f32_16x16x32_bf16 v[170:173], v[54:57], v[86:89], v[130:133]
	v_mfma_f32_16x16x32_bf16 v[130:133], v[42:45], v[114:117], v[158:161]
	v_mfma_f32_16x16x32_bf16 v[158:161], v[46:49], v[118:121], v[130:133]
	v_mfma_f32_16x16x32_bf16 v[130:133], v[50:53], v[114:117], v[154:157]
	v_mfma_f32_16x16x32_bf16 v[154:157], v[54:57], v[118:121], v[130:133]
	v_mfma_f32_16x16x32_bf16 v[130:133], v[42:45], v[122:125], v[150:153]
	v_mfma_f32_16x16x32_bf16 v[2:5], v[42:45], v[138:141], v[2:5]
	v_mfma_f32_16x16x32_bf16 v[150:153], v[46:49], v[126:129], v[130:133]
	v_mfma_f32_16x16x32_bf16 v[130:133], v[50:53], v[122:125], v[146:149]
	v_mfma_f32_16x16x32_bf16 v[134:137], v[46:49], v[142:145], v[2:5]
	v_mfma_f32_16x16x32_bf16 v[2:5], v[50:53], v[138:141], v[6:9]
	v_mfma_f32_16x16x32_bf16 v[146:149], v[54:57], v[126:129], v[130:133]
	v_mfma_f32_16x16x32_bf16 v[130:133], v[54:57], v[142:145], v[2:5]
	s_setprio 0
	s_setprio 1
	v_mfma_f32_16x16x32_bf16 v[2:5], v[66:69], v[82:85], v[34:37]
	v_mfma_f32_16x16x32_bf16 v[46:49], v[70:73], v[86:89], v[2:5]
	v_mfma_f32_16x16x32_bf16 v[2:5], v[98:101], v[82:85], v[38:41]
	v_mfma_f32_16x16x32_bf16 v[42:45], v[102:105], v[86:89], v[2:5]
	v_mfma_f32_16x16x32_bf16 v[2:5], v[66:69], v[114:117], v[30:33]
	v_mfma_f32_16x16x32_bf16 v[30:33], v[70:73], v[118:121], v[2:5]
	v_mfma_f32_16x16x32_bf16 v[2:5], v[98:101], v[114:117], v[26:29]
	v_mfma_f32_16x16x32_bf16 v[26:29], v[102:105], v[118:121], v[2:5]
	v_mfma_f32_16x16x32_bf16 v[2:5], v[66:69], v[122:125], v[22:25]
	v_mfma_f32_16x16x32_bf16 v[22:25], v[70:73], v[126:129], v[2:5]
	v_mfma_f32_16x16x32_bf16 v[2:5], v[98:101], v[122:125], v[18:21]
	v_mfma_f32_16x16x32_bf16 v[18:21], v[102:105], v[126:129], v[2:5]
	v_mfma_f32_16x16x32_bf16 v[2:5], v[66:69], v[138:141], v[14:17]
	v_mfma_f32_16x16x32_bf16 v[14:17], v[70:73], v[142:145], v[2:5]
	v_mfma_f32_16x16x32_bf16 v[2:5], v[98:101], v[138:141], v[10:13]
	v_mfma_f32_16x16x32_bf16 v[10:13], v[102:105], v[142:145], v[2:5]
	s_setprio 0
	s_barrier
	s_add_i32 s38, s38, 2
	s_add_u32 s34, s34, 0x100
	s_addc_u32 s35, s35, 0
	s_add_u32 s10, s10, 0x100
	s_addc_u32 s11, s11, 0
	s_cmp_gt_u32 s38, 13
